# adds: HGRN2 unit: third barrier lets image writes overlap the MFMA stage; spurious vmcnt ladder in the operand-image waves removed
# speedup vs baseline: 1.0263x; 1.0011x over previous
.LBB0_811:
	s_waitcnt lgkmcnt(0)
	s_barrier
	v_sub_co_u32_e64 v1, s[0:1], s49, 1
	s_nop 0
	v_readfirstlane_b32 s33, v1
	s_and_b32 s33, s33, 1
	s_mul_i32 s72, s33, 0x11000
	s_add_i32 s72, s72, 0
	s_and_b64 vcc, exec, s[0:1]
	s_cbranch_vccnz .LBB0_813
	v_add3_u32 v1, s72, v141, v145
	ds_read_b128 v[68:71], v1
	ds_read_b128 v[88:91], v1 offset:32
	v_cvt_pk_bf16_f32 v84, v52, v53
	v_cvt_pk_bf16_f32 v85, v54, v55
	v_cvt_pk_bf16_f32 v86, v56, v57
	v_cvt_pk_bf16_f32 v87, v58, v59
	v_cvt_pk_bf16_f32 v100, v60, v61
	v_cvt_pk_bf16_f32 v101, v62, v63
	v_cvt_pk_bf16_f32 v102, v64, v65
	s_waitcnt lgkmcnt(1)
	v_mfma_f32_32x32x16_bf16 v[68:83], v[68:71], v[84:87], 0
	v_cvt_pk_bf16_f32 v103, v66, v67
	s_mul_i32 vcc_lo, s33, 0xa00
	s_waitcnt lgkmcnt(0)
	v_mfma_f32_32x32x16_bf16 v[68:83], v[88:91], v[100:103], v[68:83]
	ds_read_b128 v[88:91], v1 offset:8704
	global_load_dwordx4 v[116:119], v[134:135], off offset:16
	global_load_dwordx4 v[120:123], v[134:135], off
	ds_read_b128 v[104:107], v1 offset:8736
	global_load_dwordx4 v[124:127], v[134:135], off offset:-16
	global_load_dwordx4 v[128:131], v[134:135], off offset:-32
	s_waitcnt lgkmcnt(1)
	v_mfma_f32_32x32x16_bf16 v[84:99], v[88:91], v[84:87], 0
	s_waitcnt lgkmcnt(0)
	v_mfma_f32_32x32x16_bf16 v[84:99], v[104:107], v[100:103], v[84:99]
	ds_read_b128 v[100:103], v1 offset:64
	v_cvt_pk_bf16_f32 v104, v36, v37
	v_cvt_pk_bf16_f32 v105, v38, v39
	v_cvt_pk_bf16_f32 v106, v40, v41
	v_cvt_pk_bf16_f32 v107, v42, v43
	v_cvt_pk_bf16_f32 v108, v44, v45
	v_cvt_pk_bf16_f32 v109, v46, v47
	v_cvt_pk_bf16_f32 v110, v48, v49
	v_cvt_pk_bf16_f32 v111, v50, v51
	s_waitcnt lgkmcnt(0)
	v_mfma_f32_32x32x16_bf16 v[68:83], v[100:103], v[104:107], v[68:83]
	ds_read_b128 v[100:103], v1 offset:96
	s_waitcnt lgkmcnt(0)
	v_mfma_f32_32x32x16_bf16 v[68:83], v[100:103], v[108:111], v[68:83]
	ds_read_b128 v[100:103], v1 offset:8768
	s_waitcnt lgkmcnt(0)
	v_mfma_f32_32x32x16_bf16 v[84:99], v[100:103], v[104:107], v[84:99]
	ds_read_b128 v[100:103], v1 offset:8800
	s_waitcnt lgkmcnt(0)
	v_mfma_f32_32x32x16_bf16 v[84:99], v[100:103], v[108:111], v[84:99]
	ds_read_b128 v[100:103], v1 offset:128
	v_cvt_pk_bf16_f32 v104, v20, v21
	v_cvt_pk_bf16_f32 v105, v22, v23
	v_cvt_pk_bf16_f32 v106, v24, v25
	v_cvt_pk_bf16_f32 v107, v26, v27
	v_cvt_pk_bf16_f32 v108, v28, v29
	v_cvt_pk_bf16_f32 v109, v30, v31
	v_cvt_pk_bf16_f32 v110, v32, v33
	v_cvt_pk_bf16_f32 v111, v34, v35
	s_waitcnt lgkmcnt(0)
	v_mfma_f32_32x32x16_bf16 v[68:83], v[100:103], v[104:107], v[68:83]
	ds_read_b128 v[100:103], v1 offset:160
	s_waitcnt lgkmcnt(0)
	v_mfma_f32_32x32x16_bf16 v[68:83], v[100:103], v[108:111], v[68:83]
	ds_read_b128 v[100:103], v1 offset:8832
	s_waitcnt lgkmcnt(0)
	v_mfma_f32_32x32x16_bf16 v[84:99], v[100:103], v[104:107], v[84:99]
	ds_read_b128 v[100:103], v1 offset:8864
	s_waitcnt lgkmcnt(0)
	v_mfma_f32_32x32x16_bf16 v[84:99], v[100:103], v[108:111], v[84:99]
	ds_read_b128 v[100:103], v1 offset:192
	v_cvt_pk_bf16_f32 v104, v4, v5
	v_cvt_pk_bf16_f32 v105, v6, v7
	v_cvt_pk_bf16_f32 v106, v8, v9
	v_cvt_pk_bf16_f32 v107, v10, v11
	v_cvt_pk_bf16_f32 v108, v12, v13
	v_cvt_pk_bf16_f32 v109, v14, v15
	v_cvt_pk_bf16_f32 v110, v16, v17
	v_cvt_pk_bf16_f32 v111, v18, v19
	s_waitcnt lgkmcnt(0)
	v_mfma_f32_32x32x16_bf16 v[68:83], v[100:103], v[104:107], v[68:83]
	ds_read_b128 v[100:103], v1 offset:224
	s_waitcnt lgkmcnt(0)
	v_mfma_f32_32x32x16_bf16 v[68:83], v[100:103], v[108:111], v[68:83]
	ds_read_b128 v[100:103], v1 offset:8896
	s_waitcnt lgkmcnt(0)
	v_mfma_f32_32x32x16_bf16 v[84:99], v[100:103], v[104:107], v[84:99]
	ds_read_b128 v[100:103], v1 offset:8928
	s_waitcnt lgkmcnt(0)
	v_mfma_f32_32x32x16_bf16 v[84:99], v[100:103], v[108:111], v[84:99]
	v_add3_u32 v3, s72, v145, v141
	ds_read_b128 v[100:103], v3 offset:34816
	ds_read_b128 v[104:107], v3 offset:17408
	ds_read_b128 v[168:171], v3 offset:17440
	ds_read_b128 v[172:175], v3 offset:34848
	v_add_u32_e32 v1, s72, v144
	v_add_u32_e32 v2, v1, v143
	s_waitcnt lgkmcnt(2)
	v_mfma_f32_32x32x16_bf16 v[100:115], v[100:103], v[104:107], 0
	s_waitcnt lgkmcnt(0)
	v_mfma_f32_32x32x16_bf16 v[100:115], v[172:175], v[168:171], v[100:115]
	ds_read_b128 v[168:171], v3 offset:34880
	ds_read_b128 v[172:175], v3 offset:17472
	s_waitcnt lgkmcnt(0)
	v_mfma_f32_32x32x16_bf16 v[100:115], v[168:171], v[172:175], v[100:115]
	ds_read_b128 v[168:171], v3 offset:34912
	ds_read_b128 v[172:175], v3 offset:17504
	s_waitcnt lgkmcnt(0)
	v_mfma_f32_32x32x16_bf16 v[100:115], v[168:171], v[172:175], v[100:115]
	ds_read_b128 v[168:171], v3 offset:34944
	ds_read_b128 v[172:175], v3 offset:17536
	s_waitcnt lgkmcnt(0)
	v_mfma_f32_32x32x16_bf16 v[100:115], v[168:171], v[172:175], v[100:115]
	ds_read_b128 v[168:171], v3 offset:34976
	ds_read_b128 v[172:175], v3 offset:17568
	s_waitcnt lgkmcnt(0)
	v_mfma_f32_32x32x16_bf16 v[100:115], v[168:171], v[172:175], v[100:115]
	ds_read_b128 v[168:171], v3 offset:35008
	ds_read_b128 v[172:175], v3 offset:17600
	s_waitcnt lgkmcnt(0)
	v_mfma_f32_32x32x16_bf16 v[100:115], v[168:171], v[172:175], v[100:115]
	ds_read_b128 v[168:171], v3 offset:35040
	ds_read_b128 v[172:175], v3 offset:17632
	s_waitcnt lgkmcnt(0)
	v_mfma_f32_32x32x16_bf16 v[100:115], v[168:171], v[172:175], v[100:115]
	s_nop 11
	v_cndmask_b32_e64 v167, v100, 0, s[36:37]
	v_cndmask_b32_e64 v100, v167, v100, s[34:35]
	v_cndmask_b32_e64 v101, 0, v101, s[34:35]
	v_cndmask_b32_e64 v102, v102, 0, s[30:31]
	v_cndmask_b32_e64 v103, v103, 0, s[28:29]
	v_cndmask_b32_e64 v104, v104, 0, s[26:27]
	v_cndmask_b32_e64 v105, v105, 0, s[24:25]
	v_cndmask_b32_e64 v106, v106, 0, s[22:23]
	v_cndmask_b32_e64 v107, v107, 0, s[20:21]
	v_add_u32_e32 v167, v2, v146
	v_cvt_pk_bf16_f32 v100, v100, v101
	v_cvt_pk_bf16_f32 v101, v102, v103
	v_cvt_pk_bf16_f32 v102, v104, v105
	v_cvt_pk_bf16_f32 v103, v106, v107
	ds_read_b64_tr_b16 v[104:105], v167 offset:52224
	ds_read_b64_tr_b16 v[106:107], v167 offset:54272
	s_waitcnt lgkmcnt(0)
	v_mfma_f32_32x32x16_bf16 v[68:83], v[100:103], v[104:107], v[68:83]
	v_cndmask_b32_e64 v108, v108, 0, s[18:19]
	v_cndmask_b32_e64 v109, v109, 0, s[16:17]
	v_cndmask_b32_e64 v110, v110, 0, s[14:15]
	v_cndmask_b32_e64 v111, v111, 0, s[12:13]
	v_cndmask_b32_e64 v112, v112, 0, s[10:11]
	v_cndmask_b32_e64 v113, v113, 0, s[8:9]
	v_cndmask_b32_e64 v114, v114, 0, s[6:7]
	v_cndmask_b32_e64 v115, v115, 0, s[4:5]
	v_cvt_pk_bf16_f32 v100, v108, v109
	v_cvt_pk_bf16_f32 v101, v110, v111
	v_cvt_pk_bf16_f32 v102, v112, v113
	v_cvt_pk_bf16_f32 v103, v114, v115
	ds_read_b64_tr_b16 v[104:105], v167 offset:56320
	ds_read_b64_tr_b16 v[106:107], v167 offset:58368
	s_waitcnt lgkmcnt(0)
	v_mfma_f32_32x32x16_bf16 v[68:83], v[100:103], v[104:107], v[68:83]
	v_add_u32_e32 v180, 0xcc00, v167
	ds_read_b128 v[100:103], v3 offset:34816
	ds_read_b128 v[104:107], v3 offset:26112
	ds_read_b128 v[168:171], v3 offset:34848
	ds_read_b128 v[172:175], v3 offset:26144
	s_waitcnt lgkmcnt(2)
	v_mfma_f32_32x32x16_bf16 v[100:115], v[100:103], v[104:107], 0
	s_waitcnt lgkmcnt(0)
	v_mfma_f32_32x32x16_bf16 v[100:115], v[168:171], v[172:175], v[100:115]
	ds_read_b128 v[168:171], v3 offset:34880
	ds_read_b128 v[172:175], v3 offset:26176
	s_waitcnt lgkmcnt(0)
	v_mfma_f32_32x32x16_bf16 v[100:115], v[168:171], v[172:175], v[100:115]
	ds_read_b128 v[168:171], v3 offset:34912
	ds_read_b128 v[172:175], v3 offset:26208
	s_waitcnt lgkmcnt(0)
	v_mfma_f32_32x32x16_bf16 v[100:115], v[168:171], v[172:175], v[100:115]
	ds_read_b128 v[168:171], v3 offset:34944
	ds_read_b128 v[172:175], v3 offset:26240
	s_waitcnt lgkmcnt(0)
	v_mfma_f32_32x32x16_bf16 v[100:115], v[168:171], v[172:175], v[100:115]
	ds_read_b128 v[168:171], v3 offset:34976
	ds_read_b128 v[172:175], v3 offset:26272
	s_waitcnt lgkmcnt(0)
	v_mfma_f32_32x32x16_bf16 v[100:115], v[168:171], v[172:175], v[100:115]
	ds_read_b128 v[168:171], v3 offset:35008
	ds_read_b128 v[172:175], v3 offset:26304
	s_waitcnt lgkmcnt(0)
	v_mfma_f32_32x32x16_bf16 v[100:115], v[168:171], v[172:175], v[100:115]
	ds_read_b128 v[168:171], v3 offset:35040
	ds_read_b128 v[172:175], v3 offset:26336
	s_waitcnt lgkmcnt(0)
	v_mfma_f32_32x32x16_bf16 v[100:115], v[168:171], v[172:175], v[100:115]
	ds_read_b64_tr_b16 v[168:169], v167 offset:52224
	ds_read_b64_tr_b16 v[170:171], v167 offset:54272
	s_nop 9
	v_cvt_pk_bf16_f32 v100, v100, v101
	v_cvt_pk_bf16_f32 v101, v102, v103
	v_cvt_pk_bf16_f32 v102, v104, v105
	v_cvt_pk_bf16_f32 v103, v106, v107
	ds_read_b64_tr_b16 v[104:105], v167 offset:56320
	ds_read_b64_tr_b16 v[106:107], v167 offset:58368
	s_waitcnt lgkmcnt(2)
	v_mfma_f32_32x32x16_bf16 v[84:99], v[100:103], v[168:171], v[84:99]
	v_cvt_pk_bf16_f32 v100, v108, v109
	v_cvt_pk_bf16_f32 v101, v110, v111
	v_cvt_pk_bf16_f32 v102, v112, v113
	v_cvt_pk_bf16_f32 v103, v114, v115
	s_waitcnt lgkmcnt(0)
	s_nop 0
	v_mfma_f32_32x32x16_bf16 v[84:99], v[100:103], v[104:107], v[84:99]
	ds_read_b128 v[100:103], v3 offset:43520
	ds_read_b128 v[104:107], v3 offset:26112
	ds_read_b128 v[168:171], v3 offset:43552
	ds_read_b128 v[172:175], v3 offset:26144
	s_waitcnt lgkmcnt(2)
	v_mfma_f32_32x32x16_bf16 v[100:115], v[100:103], v[104:107], 0
	s_waitcnt lgkmcnt(0)
	v_mfma_f32_32x32x16_bf16 v[100:115], v[168:171], v[172:175], v[100:115]
	ds_read_b128 v[168:171], v3 offset:43584
	ds_read_b128 v[172:175], v3 offset:26176
	s_waitcnt lgkmcnt(0)
	v_mfma_f32_32x32x16_bf16 v[100:115], v[168:171], v[172:175], v[100:115]
	ds_read_b128 v[168:171], v3 offset:43616
	ds_read_b128 v[172:175], v3 offset:26208
	s_waitcnt lgkmcnt(0)
	v_mfma_f32_32x32x16_bf16 v[100:115], v[168:171], v[172:175], v[100:115]
	ds_read_b128 v[168:171], v3 offset:43648
	ds_read_b128 v[172:175], v3 offset:26240
	s_waitcnt lgkmcnt(0)
	v_mfma_f32_32x32x16_bf16 v[100:115], v[168:171], v[172:175], v[100:115]
	ds_read_b128 v[168:171], v3 offset:43680
	ds_read_b128 v[172:175], v3 offset:26272
	s_waitcnt lgkmcnt(0)
	v_mfma_f32_32x32x16_bf16 v[100:115], v[168:171], v[172:175], v[100:115]
	ds_read_b128 v[168:171], v3 offset:43712
	ds_read_b128 v[172:175], v3 offset:26304
	s_waitcnt lgkmcnt(0)
	v_mfma_f32_32x32x16_bf16 v[100:115], v[168:171], v[172:175], v[100:115]
	ds_read_b128 v[168:171], v3 offset:43744
	ds_read_b128 v[172:175], v3 offset:26336
	ds_read_b64_tr_b16 v[176:177], v167 offset:60416
	ds_read_b64_tr_b16 v[178:179], v167 offset:62464
	s_waitcnt lgkmcnt(2)
	v_mfma_f32_32x32x16_bf16 v[100:115], v[168:171], v[172:175], v[100:115]
	s_nop 11
	v_cndmask_b32_e64 v3, v100, 0, s[36:37]
	v_cndmask_b32_e64 v168, 0, v101, s[34:35]
	v_cndmask_b32_e64 v101, v102, 0, s[30:31]
	v_cndmask_b32_e64 v102, v103, 0, s[28:29]
	v_cndmask_b32_e64 v103, v104, 0, s[26:27]
	v_cndmask_b32_e64 v104, v105, 0, s[24:25]
	v_cndmask_b32_e64 v105, v106, 0, s[22:23]
	v_cndmask_b32_e64 v106, v107, 0, s[20:21]
	v_cndmask_b32_e64 v3, v3, v100, s[34:35]
	v_cvt_pk_bf16_f32 v101, v101, v102
	v_cvt_pk_bf16_f32 v102, v103, v104
	v_cvt_pk_bf16_f32 v103, v105, v106
	v_cvt_pk_bf16_f32 v100, v3, v168
	v_cndmask_b32_e64 v107, v108, 0, s[18:19]
	v_cndmask_b32_e64 v108, v109, 0, s[16:17]
	s_waitcnt lgkmcnt(0)
	v_mfma_f32_32x32x16_bf16 v[84:99], v[100:103], v[176:179], v[84:99]
	v_cndmask_b32_e64 v109, v110, 0, s[14:15]
	v_cndmask_b32_e64 v110, v111, 0, s[12:13]
	v_cndmask_b32_e64 v111, v112, 0, s[10:11]
	v_cndmask_b32_e64 v112, v113, 0, s[8:9]
	v_cndmask_b32_e64 v3, v114, 0, s[6:7]
	v_cndmask_b32_e64 v113, v115, 0, s[4:5]
	v_cvt_pk_bf16_f32 v104, v107, v108
	v_cvt_pk_bf16_f32 v105, v109, v110
	v_cvt_pk_bf16_f32 v106, v111, v112
	v_cvt_pk_bf16_f32 v107, v3, v113
	ds_read_b64_tr_b16 v[100:101], v167 offset:64512
	ds_read_b64_tr_b16 v[102:103], v180 offset:14336
	s_waitcnt lgkmcnt(0)
	v_mfma_f32_32x32x16_bf16 v[84:99], v[104:107], v[100:103], v[84:99]
	v_add_u32_e32 v3, vcc_lo, v166
	ds_read_b128 v[100:103], v3 offset:2048
	ds_read_b128 v[104:107], v3 offset:2080
	ds_read_b128 v[108:111], v3 offset:2112
	ds_read_b128 v[112:115], v3 offset:2144
	s_waitcnt lgkmcnt(3)
	v_pk_mul_f32 v[54:55], v[54:55], v[102:103]
	s_waitcnt lgkmcnt(2)
	v_pk_mul_f32 v[56:57], v[56:57], v[104:105]
	s_waitcnt lgkmcnt(1)
	v_pk_mul_f32 v[60:61], v[60:61], v[108:109]
	s_waitcnt lgkmcnt(0)
	v_pk_mul_f32 v[64:65], v[64:65], v[112:113]
	v_pk_mul_f32 v[66:67], v[66:67], v[114:115]
	v_pk_mul_f32 v[62:63], v[62:63], v[110:111]
	v_pk_mul_f32 v[58:59], v[58:59], v[106:107]
	v_pk_mul_f32 v[52:53], v[52:53], v[100:101]
	ds_read_b128 v[100:103], v3 offset:2176
	ds_read_b128 v[104:107], v3 offset:2208
	ds_read_b128 v[108:111], v3 offset:2240
	ds_read_b128 v[112:115], v3 offset:2272
	s_waitcnt lgkmcnt(3)
	v_pk_mul_f32 v[38:39], v[38:39], v[102:103]
	s_waitcnt lgkmcnt(2)
	v_pk_mul_f32 v[40:41], v[40:41], v[104:105]
	s_waitcnt lgkmcnt(1)
	v_pk_mul_f32 v[44:45], v[44:45], v[108:109]
	s_waitcnt lgkmcnt(0)
	v_pk_mul_f32 v[48:49], v[48:49], v[112:113]
	v_pk_mul_f32 v[50:51], v[50:51], v[114:115]
	v_pk_mul_f32 v[46:47], v[46:47], v[110:111]
	v_pk_mul_f32 v[42:43], v[42:43], v[106:107]
	v_pk_mul_f32 v[36:37], v[36:37], v[100:101]
	ds_read_b128 v[100:103], v3 offset:2304
	ds_read_b128 v[104:107], v3 offset:2336
	ds_read_b128 v[108:111], v3 offset:2368
	ds_read_b128 v[112:115], v3 offset:2400
	s_waitcnt lgkmcnt(3)
	v_pk_mul_f32 v[22:23], v[22:23], v[102:103]
	s_waitcnt lgkmcnt(2)
	v_pk_mul_f32 v[24:25], v[24:25], v[104:105]
	s_waitcnt lgkmcnt(1)
	v_pk_mul_f32 v[28:29], v[28:29], v[108:109]
	s_waitcnt lgkmcnt(0)
	v_pk_mul_f32 v[32:33], v[32:33], v[112:113]
	v_pk_mul_f32 v[34:35], v[34:35], v[114:115]
	v_pk_mul_f32 v[30:31], v[30:31], v[110:111]
	v_pk_mul_f32 v[26:27], v[26:27], v[106:107]
	v_pk_mul_f32 v[20:21], v[20:21], v[100:101]
	ds_read_b128 v[100:103], v3 offset:2432
	ds_read_b128 v[104:107], v3 offset:2464
	ds_read_b128 v[108:111], v3 offset:2496
	ds_read_b128 v[112:115], v3 offset:2528
	v_add_u32_e32 v3, v2, v147
	s_waitcnt lgkmcnt(3)
	v_pk_mul_f32 v[4:5], v[4:5], v[100:101]
	s_waitcnt lgkmcnt(2)
	v_pk_mul_f32 v[10:11], v[10:11], v[106:107]
	s_waitcnt lgkmcnt(1)
	v_pk_mul_f32 v[12:13], v[12:13], v[108:109]
	v_add_u32_e32 v108, v1, v150
	v_pk_mul_f32 v[14:15], v[14:15], v[110:111]
	v_add_u32_e32 v110, v108, v142
	ds_read_b64_tr_b16 v[100:101], v3 offset:52224
	ds_read_b64_tr_b16 v[106:107], v110 offset:34816
	v_add_u32_e32 v3, v2, v148
	v_pk_mul_f32 v[6:7], v[6:7], v[102:103]
	ds_read_b64_tr_b16 v[102:103], v3 offset:52224
	v_add_u32_e32 v3, v1, v149
	v_add_u32_e32 v109, v3, v142
	v_pk_mul_f32 v[8:9], v[8:9], v[104:105]
	ds_read_b64_tr_b16 v[104:105], v109 offset:34816
	s_waitcnt lgkmcnt(0)
	v_mfma_f32_32x32x16_bf16 v[52:67], v[104:107], v[100:103], v[52:67]
	v_add_u32_e32 v104, v3, v151
	v_add_u32_e32 v106, v108, v151
	ds_read_b64_tr_b16 v[104:105], v104 offset:34816
	ds_read_b64_tr_b16 v[106:107], v106 offset:34816
	v_add_u32_e32 v3, v3, v152
	v_pk_mul_f32 v[16:17], v[16:17], v[112:113]
	v_pk_mul_f32 v[18:19], v[18:19], v[114:115]
	s_waitcnt lgkmcnt(0)
	v_mfma_f32_32x32x16_bf16 v[36:51], v[104:107], v[100:103], v[36:51]
	ds_read_b64_tr_b16 v[104:105], v109 offset:34944
	ds_read_b64_tr_b16 v[106:107], v110 offset:34944
	s_waitcnt lgkmcnt(0)
	v_mfma_f32_32x32x16_bf16 v[20:35], v[104:107], v[100:103], v[20:35]
	ds_read_b64_tr_b16 v[104:105], v3 offset:34816
	v_add_u32_e32 v3, v108, v152
	ds_read_b64_tr_b16 v[106:107], v3 offset:34816
	s_waitcnt lgkmcnt(0)
	v_mfma_f32_32x32x16_bf16 v[4:19], v[104:107], v[100:103], v[4:19]
	v_add_u32_e32 v108, v1, v156
	v_add_u32_e32 v3, v2, v153
	v_add_u32_e32 v110, v108, v142
	ds_read_b64_tr_b16 v[100:101], v3 offset:52224
	ds_read_b64_tr_b16 v[106:107], v110 offset:34816
	v_add_u32_e32 v3, v2, v154
	ds_read_b64_tr_b16 v[102:103], v3 offset:52224
	v_add_u32_e32 v3, v1, v155
	v_add_u32_e32 v109, v3, v142
	ds_read_b64_tr_b16 v[104:105], v109 offset:34816
	s_waitcnt lgkmcnt(0)
	v_mfma_f32_32x32x16_bf16 v[52:67], v[104:107], v[100:103], v[52:67]
	v_add_u32_e32 v104, v3, v151
	v_add_u32_e32 v106, v108, v151
	ds_read_b64_tr_b16 v[104:105], v104 offset:34816
	ds_read_b64_tr_b16 v[106:107], v106 offset:34816
	v_add_u32_e32 v3, v3, v152
	s_waitcnt lgkmcnt(0)
	v_mfma_f32_32x32x16_bf16 v[36:51], v[104:107], v[100:103], v[36:51]
	ds_read_b64_tr_b16 v[104:105], v109 offset:34944
	ds_read_b64_tr_b16 v[106:107], v110 offset:34944
	s_waitcnt lgkmcnt(0)
	v_mfma_f32_32x32x16_bf16 v[20:35], v[104:107], v[100:103], v[20:35]
	ds_read_b64_tr_b16 v[104:105], v3 offset:34816
	v_add_u32_e32 v3, v108, v152
	ds_read_b64_tr_b16 v[106:107], v3 offset:34816
	s_waitcnt lgkmcnt(0)
	v_mfma_f32_32x32x16_bf16 v[4:19], v[104:107], v[100:103], v[4:19]
	v_add_u32_e32 v108, v1, v160
	v_add_u32_e32 v3, v2, v157
	v_add_u32_e32 v110, v108, v142
	ds_read_b64_tr_b16 v[100:101], v3 offset:52224
	ds_read_b64_tr_b16 v[106:107], v110 offset:34816
	v_add_u32_e32 v3, v2, v158
	ds_read_b64_tr_b16 v[102:103], v3 offset:52224
	v_add_u32_e32 v3, v1, v159
	v_add_u32_e32 v109, v3, v142
	ds_read_b64_tr_b16 v[104:105], v109 offset:34816
	s_waitcnt lgkmcnt(0)
	v_mfma_f32_32x32x16_bf16 v[52:67], v[104:107], v[100:103], v[52:67]
	v_add_u32_e32 v104, v3, v151
	v_add_u32_e32 v106, v108, v151
	ds_read_b64_tr_b16 v[104:105], v104 offset:34816
	ds_read_b64_tr_b16 v[106:107], v106 offset:34816
	v_add_u32_e32 v3, v3, v152
	s_waitcnt lgkmcnt(0)
	v_mfma_f32_32x32x16_bf16 v[36:51], v[104:107], v[100:103], v[36:51]
	ds_read_b64_tr_b16 v[104:105], v109 offset:34944
	ds_read_b64_tr_b16 v[106:107], v110 offset:34944
	s_waitcnt lgkmcnt(0)
	v_mfma_f32_32x32x16_bf16 v[20:35], v[104:107], v[100:103], v[20:35]
	ds_read_b64_tr_b16 v[104:105], v3 offset:34816
	v_add_u32_e32 v3, v108, v152
	ds_read_b64_tr_b16 v[106:107], v3 offset:34816
	s_waitcnt lgkmcnt(0)
	v_mfma_f32_32x32x16_bf16 v[4:19], v[104:107], v[100:103], v[4:19]
	v_add_u32_e32 v3, v2, v161
	v_add_u32_e32 v2, v2, v162
	ds_read_b64_tr_b16 v[100:101], v3 offset:52224
	ds_read_b64_tr_b16 v[102:103], v2 offset:52224
	v_add_u32_e32 v2, v1, v163
	v_add_u32_e32 v1, v1, v164
	v_add_u32_e32 v3, v2, v142
	v_add_u32_e32 v108, v1, v142
	ds_read_b64_tr_b16 v[104:105], v3 offset:34816
	ds_read_b64_tr_b16 v[106:107], v108 offset:34816
	s_waitcnt lgkmcnt(0)
	v_mfma_f32_32x32x16_bf16 v[52:67], v[104:107], v[100:103], v[52:67]
	v_add_u32_e32 v104, v2, v151
	v_add_u32_e32 v106, v1, v151
	ds_read_b64_tr_b16 v[104:105], v104 offset:34816
	ds_read_b64_tr_b16 v[106:107], v106 offset:34816
	v_add_u32_e32 v2, v2, v152
	v_add_u32_e32 v1, v1, v152
	s_waitcnt lgkmcnt(0)
	v_mfma_f32_32x32x16_bf16 v[36:51], v[104:107], v[100:103], v[36:51]
	ds_read_b64_tr_b16 v[104:105], v3 offset:34944
	ds_read_b64_tr_b16 v[106:107], v108 offset:34944
	s_waitcnt lgkmcnt(0)
	v_mfma_f32_32x32x16_bf16 v[20:35], v[104:107], v[100:103], v[20:35]
	ds_read_b64_tr_b16 v[104:105], v2 offset:34816
	ds_read_b64_tr_b16 v[106:107], v1 offset:34816
	s_waitcnt lgkmcnt(0)
	v_mfma_f32_32x32x16_bf16 v[4:19], v[104:107], v[100:103], v[4:19]

.LBB0_866:
	s_and_b64 vcc, exec, s[0:1]
	s_cbranch_vccz .LBB0_756
	s_lshr_b32 s72, s68, 6
	s_lshl_b32 s6, s72, 4
	v_lshlrev_b32_e32 v1, 1, v138
	v_or_b32_e32 v2, s69, v1
	s_or_b32 s0, s6, s84
	s_mov_b32 s1, s85
	s_or_b32 s15, s6, 1
	s_lshl_b64 s[4:5], s[0:1], 10
	v_lshlrev_b32_e32 v2, 1, v2
	s_or_b32 s84, s84, s15
	v_or_b32_e32 v4, s4, v2
	s_waitcnt lgkmcnt(0)
	v_mov_b32_e32 v5, s5
	s_lshl_b64 s[4:5], s[84:85], 10
	s_or_b32 s84, s0, 2
	v_or_b32_e32 v8, s4, v2
	v_mov_b32_e32 v9, s5
	s_lshl_b64 s[4:5], s[84:85], 10
	s_or_b32 s84, s0, 3
	v_or_b32_e32 v12, s4, v2
	v_mov_b32_e32 v13, s5
	s_lshl_b64 s[4:5], s[84:85], 10
	s_or_b32 s84, s0, 4
	v_lshl_add_u64 v[6:7], s[50:51], 0, v[4:5]
	v_lshl_add_u64 v[4:5], s[46:47], 0, v[4:5]
	v_or_b32_e32 v16, s4, v2
	v_mov_b32_e32 v17, s5
	s_lshl_b64 s[4:5], s[84:85], 10
	s_or_b32 s84, s0, 5
	v_lshl_add_u64 v[10:11], s[50:51], 0, v[8:9]
	v_lshl_add_u64 v[8:9], s[46:47], 0, v[8:9]
	v_lshl_add_u64 v[14:15], s[50:51], 0, v[12:13]
	v_lshl_add_u64 v[12:13], s[46:47], 0, v[12:13]
	v_lshl_add_u64 v[18:19], s[50:51], 0, v[16:17]
	v_lshl_add_u64 v[16:17], s[46:47], 0, v[16:17]
	global_load_dword v110, v[6:7], off
	global_load_dword v107, v[4:5], off
	global_load_dword v105, v[10:11], off
	global_load_dword v101, v[8:9], off
	global_load_dword v100, v[14:15], off
	global_load_dword v97, v[12:13], off
	global_load_dword v96, v[18:19], off
	global_load_dword v93, v[16:17], off
	v_or_b32_e32 v4, s4, v2
	v_mov_b32_e32 v5, s5
	s_lshl_b64 s[4:5], s[84:85], 10
	s_or_b32 s84, s0, 6
	v_or_b32_e32 v8, s4, v2
	v_mov_b32_e32 v9, s5
	s_lshl_b64 s[4:5], s[84:85], 10
	s_or_b32 s84, s0, 7
	v_or_b32_e32 v12, s4, v2
	v_mov_b32_e32 v13, s5
	s_lshl_b64 s[4:5], s[84:85], 10
	s_or_b32 s84, s0, 8
	v_lshl_add_u64 v[6:7], s[50:51], 0, v[4:5]
	v_lshl_add_u64 v[4:5], s[46:47], 0, v[4:5]
	v_or_b32_e32 v16, s4, v2
	v_mov_b32_e32 v17, s5
	s_lshl_b64 s[4:5], s[84:85], 10
	s_or_b32 s84, s0, 9
	v_lshl_add_u64 v[10:11], s[50:51], 0, v[8:9]
	v_lshl_add_u64 v[8:9], s[46:47], 0, v[8:9]
	v_lshl_add_u64 v[14:15], s[50:51], 0, v[12:13]
	v_lshl_add_u64 v[12:13], s[46:47], 0, v[12:13]
	v_lshl_add_u64 v[18:19], s[50:51], 0, v[16:17]
	v_lshl_add_u64 v[16:17], s[46:47], 0, v[16:17]
	global_load_dword v98, v[6:7], off
	global_load_dword v95, v[4:5], off
	global_load_dword v94, v[10:11], off
	global_load_dword v92, v[8:9], off
	global_load_dword v91, v[14:15], off
	global_load_dword v90, v[12:13], off
	global_load_dword v89, v[18:19], off
	global_load_dword v86, v[16:17], off
	v_or_b32_e32 v4, s4, v2
	v_mov_b32_e32 v5, s5
	s_lshl_b64 s[4:5], s[84:85], 10
	s_or_b32 s84, s0, 10
	v_or_b32_e32 v8, s4, v2
	v_mov_b32_e32 v9, s5
	s_lshl_b64 s[4:5], s[84:85], 10
	s_or_b32 s84, s0, 11
	v_or_b32_e32 v12, s4, v2
	v_mov_b32_e32 v13, s5
	s_lshl_b64 s[4:5], s[84:85], 10
	s_or_b32 s84, s0, 12
	v_lshl_add_u64 v[6:7], s[50:51], 0, v[4:5]
	v_lshl_add_u64 v[4:5], s[46:47], 0, v[4:5]
	v_or_b32_e32 v16, s4, v2
	v_mov_b32_e32 v17, s5
	s_lshl_b64 s[4:5], s[84:85], 10
	s_or_b32 s84, s0, 13
	v_lshl_add_u64 v[10:11], s[50:51], 0, v[8:9]
	v_lshl_add_u64 v[8:9], s[46:47], 0, v[8:9]
	v_lshl_add_u64 v[14:15], s[50:51], 0, v[12:13]
	v_lshl_add_u64 v[12:13], s[46:47], 0, v[12:13]
	v_lshl_add_u64 v[18:19], s[50:51], 0, v[16:17]
	v_lshl_add_u64 v[16:17], s[46:47], 0, v[16:17]
	global_load_dword v88, v[6:7], off
	global_load_dword v87, v[4:5], off
	global_load_dword v84, v[10:11], off
	global_load_dword v85, v[8:9], off
	global_load_dword v71, v[14:15], off
	global_load_dword v72, v[12:13], off
	global_load_dword v48, v[18:19], off
	global_load_dword v51, v[16:17], off
	v_or_b32_e32 v4, s4, v2
	v_mov_b32_e32 v5, s5
	s_lshl_b64 s[4:5], s[84:85], 10
	s_or_b32 s84, s0, 14
	v_or_b32_e32 v8, s4, v2
	v_mov_b32_e32 v9, s5
	s_lshl_b64 s[4:5], s[84:85], 10
	s_or_b32 s84, s0, 15
	s_lshl_b64 s[0:1], s[84:85], 10
	v_lshl_add_u64 v[6:7], s[50:51], 0, v[4:5]
	v_or_b32_e32 v12, s4, v2
	v_mov_b32_e32 v13, s5
	v_or_b32_e32 v16, s0, v2
	v_mov_b32_e32 v17, s1
	v_lshl_add_u64 v[4:5], s[46:47], 0, v[4:5]
	v_lshl_add_u64 v[10:11], s[50:51], 0, v[8:9]
	v_lshl_add_u64 v[8:9], s[46:47], 0, v[8:9]
	v_lshl_add_u64 v[14:15], s[50:51], 0, v[12:13]
	v_lshl_add_u64 v[12:13], s[46:47], 0, v[12:13]
	v_lshl_add_u64 v[18:19], s[50:51], 0, v[16:17]
	v_lshl_add_u64 v[16:17], s[46:47], 0, v[16:17]
	global_load_dword v52, v[6:7], off
	global_load_dword v59, v[4:5], off
	global_load_dword v44, v[10:11], off
	global_load_dword v45, v[8:9], off
	global_load_dword v42, v[14:15], off
	global_load_dword v43, v[12:13], off
	global_load_dword v32, v[18:19], off
	global_load_dword v39, v[16:17], off
	s_lshl_b32 s12, s72, 12
	s_lshl_b32 s13, s72, 9
	v_lshlrev_b32_e32 v3, 2, v136
	s_cmp_eq_u32 s43, 0
	v_and_b32_e32 v3, 8, v3
	v_and_b32_e32 v4, 4, v136
	v_and_b32_e32 v1, 0x72, v1
	s_cselect_b64 s[0:1], -1, 0
	v_or3_b32 v1, v3, v4, v1
	s_cmp_gt_u32 s43, 1
	v_lshlrev_b32_e32 v3, 2, v138
	v_lshlrev_b32_e32 v1, 1, v1
	s_cselect_b64 s[4:5], -1, 0
	s_cmp_eq_u32 s43, 3
	s_mulk_i32 s15, 0x110
	v_and_b32_e32 v22, 12, v1
	v_and_b32_e32 v23, 0xf0, v1
	v_and_b32_e32 v1, 0xf0, v3
	s_cselect_b64 s[6:7], -1, 0
	s_add_i32 s8, s15, 0x110
	v_add_u32_e32 v26, s8, v1
	s_add_i32 s8, s15, 0x220
	v_add_u32_e32 v27, s8, v1
	s_add_i32 s8, s15, 0x330
	v_add_u32_e32 v28, s8, v1
	s_add_i32 s8, s15, 0x440
	v_add_u32_e32 v29, s8, v1
	s_add_i32 s8, s15, 0x550
	v_add_u32_e32 v30, s8, v1
	s_add_i32 s8, s15, 0x770
	v_add_u32_e32 v33, s8, v1
	s_add_i32 s8, s15, 0x880
	v_add_u32_e32 v34, s8, v1
	s_add_i32 s8, s15, 0x990
	v_add_u32_e32 v35, s8, v1
	s_add_i32 s8, s15, 0xaa0
	v_add_u32_e32 v36, s8, v1
	s_add_i32 s8, s15, 0xbb0
	v_add_u32_e32 v37, s8, v1
	s_add_i32 s8, s15, 0xdd0
	v_add_u32_e32 v40, s8, v1
	s_add_i32 s8, s15, 0xee0
	s_add_i32 s16, s15, 0x660
	s_add_i32 s17, s15, 0xcc0
	v_add_u32_e32 v41, s8, v1
	s_lshl_b64 s[8:9], s[82:83], 21
	s_lshl_b64 s[10:11], s[72:73], 14
	s_add_u32 s10, s8, s10
	s_addc_u32 s11, s9, s11
	s_add_u32 s8, s66, s10
	v_and_b32_e32 v21, 12, v3
	v_mov_b32_e32 v3, v0
	s_addc_u32 s9, s67, s11
	s_mul_i32 s14, s72, 0x1100
	v_lshl_add_u64 v[10:11], s[8:9], 0, v[2:3]
	s_and_b32 s8, s53, 3
	v_and_b32_e32 v2, 15, v136
	v_or_b32_e32 v24, s14, v1
	v_add_u32_e32 v25, s15, v1
	v_add_u32_e32 v31, s16, v1
	v_add_u32_e32 v38, s17, v1
	v_lshl_or_b32 v1, v137, 10, s10
	s_lshl_b32 s8, s8, 8
	v_lshlrev_b32_e32 v2, 4, v2
	v_or3_b32 v2, v1, s8, v2
	v_mov_b32_e32 v3, s11
	v_lshlrev_b32_e32 v20, 3, v138
	v_lshl_add_u64 v[12:13], s[70:71], 0, v[2:3]
	s_waitcnt vmcnt(0)
	v_mov_b32_e32 v62, 0
	s_mov_b64 s[8:9], 0
	s_mov_b32 s18, 0
	v_mov_b32_e32 v76, 0
	v_mov_b32_e32 v74, 0
	v_mov_b32_e32 v73, 0
	v_mov_b32_e32 v70, 0
	v_mov_b32_e32 v66, 0
	v_mov_b32_e32 v64, 0
	v_mov_b32_e32 v63, 0
	v_mov_b32_e32 v61, 0
	v_mov_b32_e32 v56, 0
	v_mov_b32_e32 v54, 0
	v_mov_b32_e32 v53, 0
	v_mov_b32_e32 v50, 0
	v_mov_b32_e32 v49, 0
	v_mov_b32_e32 v47, 0
	v_mov_b32_e32 v46, 0
	v_mov_b32_e32 v83, 0
	v_mov_b32_e32 v82, 0
	v_mov_b32_e32 v81, 0
	v_mov_b32_e32 v80, 0
	v_mov_b32_e32 v79, 0
	v_mov_b32_e32 v78, 0
	v_mov_b32_e32 v77, 0
	v_mov_b32_e32 v75, 0
	v_mov_b32_e32 v69, 0
	v_mov_b32_e32 v68, 0
	v_mov_b32_e32 v67, 0
	v_mov_b32_e32 v65, 0
	v_mov_b32_e32 v60, 0
	v_mov_b32_e32 v58, 0
	v_mov_b32_e32 v57, 0
	v_mov_b32_e32 v55, 0
	s_branch .LBB0_870
.LBB0_868:
	v_cndmask_b32_e64 v3, v3, 0, s[0:1]
	v_cndmask_b32_e64 v9, v130, 0, s[0:1]
	v_add_f32_e32 v4, v4, v9
	v_add_f32_e32 v5, v5, v3
	v_cndmask_b32_e64 v3, v3, v5, s[4:5]
	v_cndmask_b32_e64 v4, v9, v4, s[4:5]
	v_add_f32_e32 v5, v6, v4
	v_add_f32_e32 v6, v7, v3
	v_max_f32_e64 v2, -v2, -v2
	v_cndmask_b32_e64 v3, v3, v6, s[6:7]
	v_cndmask_b32_e64 v6, v4, v5, s[6:7]
	v_min_f32_e32 v2, 0x42e60000, v2
	v_exp_f32_e32 v4, v2
	v_max_f32_e64 v2, -v8, -v8
	v_add_f32_e32 v17, v18, v6
	v_min_f32_e32 v2, 0x42e60000, v2
	v_exp_f32_e32 v132, v17
	v_add_f32_e32 v17, v99, v3
	v_exp_f32_e32 v5, v2
	v_exp_f32_e32 v133, v17
	v_mul_f32_e32 v17, v4, v132
	s_nop 0
	v_lshlrev_b32_e32 v130, 16, v107
	v_and_b32_e32 v131, 0xffff0000, v107
	v_med3_f32 v134, v17, s52, v224
	v_mul_f32_e32 v17, v5, v133
	v_med3_f32 v135, v17, s52, v224
	v_pk_mul_f32 v[132:133], v[132:133], v[130:131]
	v_add3_u32 v7, s19, v23, v22
	v_cvt_pk_bf16_f32 v17, v132, v133
	v_rcp_f32_e32 v132, v134
	v_rcp_f32_e32 v133, v135
	v_lshlrev_b32_e32 v8, 16, v110
	v_and_b32_e32 v9, 0xffff0000, v110
	v_add_u32_e32 v2, s19, v21
	v_add_u32_e32 v107, s14, v7
	v_pk_mul_f32 v[130:131], v[134:135], v[130:131]
	v_pk_mul_f32 v[8:9], v[132:133], v[8:9]
	ds_write_b32 v107, v17
	v_cvt_pk_bf16_f32 v17, v130, v131
	v_add_u32_e32 v107, v2, v24
	v_cvt_pk_bf16_f32 v8, v8, v9
	ds_write2st64_b32 v107, v17, v8 offset0:68 offset1:136
	v_add_f32_e32 v17, v1, v6
	v_exp_f32_e32 v132, v17
	v_add_f32_e32 v17, v102, v3
	v_exp_f32_e32 v133, v17
	s_nop 0
	v_lshlrev_b32_e32 v130, 16, v101
	v_mul_f32_e32 v17, v4, v132
	v_and_b32_e32 v131, 0xffff0000, v101
	v_med3_f32 v134, v17, s52, v224
	v_mul_f32_e32 v17, v5, v133
	v_med3_f32 v135, v17, s52, v224
	v_pk_mul_f32 v[132:133], v[132:133], v[130:131]
	v_lshlrev_b32_e32 v8, 16, v105
	v_cvt_pk_bf16_f32 v17, v132, v133
	v_rcp_f32_e32 v132, v134
	v_rcp_f32_e32 v133, v135
	v_and_b32_e32 v9, 0xffff0000, v105
	v_add_u32_e32 v105, s15, v7
	v_pk_mul_f32 v[130:131], v[134:135], v[130:131]
	v_pk_mul_f32 v[8:9], v[132:133], v[8:9]
	ds_write_b32 v105, v17
	v_cvt_pk_bf16_f32 v17, v130, v131
	v_add_u32_e32 v101, v2, v25
	v_cvt_pk_bf16_f32 v8, v8, v9
	ds_write2st64_b32 v101, v17, v8 offset0:68 offset1:136
	v_add_f32_e32 v17, v14, v6
	v_exp_f32_e32 v130, v17
	v_add_f32_e32 v17, v103, v3
	v_exp_f32_e32 v131, v17
	s_nop 0
	v_lshlrev_b32_e32 v8, 16, v100
	v_mul_f32_e32 v17, v4, v130
	v_and_b32_e32 v9, 0xffff0000, v100
	s_nop 0
	v_lshlrev_b32_e32 v100, 16, v97
	v_and_b32_e32 v101, 0xffff0000, v97
	v_med3_f32 v132, v17, s52, v224
	v_mul_f32_e32 v17, v5, v131
	v_med3_f32 v133, v17, s52, v224
	v_pk_mul_f32 v[130:131], v[130:131], v[100:101]
	v_pk_mul_f32 v[100:101], v[132:133], v[100:101]
	v_cvt_pk_bf16_f32 v17, v130, v131
	v_rcp_f32_e32 v130, v132
	v_rcp_f32_e32 v131, v133
	ds_write_b32 v105, v17 offset:272
	v_cvt_pk_bf16_f32 v17, v100, v101
	v_add_u32_e32 v97, v2, v26
	v_pk_mul_f32 v[8:9], v[130:131], v[8:9]
	s_nop 0
	v_cvt_pk_bf16_f32 v8, v8, v9
	ds_write2st64_b32 v97, v17, v8 offset0:68 offset1:136
	v_add_f32_e32 v17, v118, v6
	v_exp_f32_e32 v100, v17
	v_add_f32_e32 v17, v104, v3
	v_exp_f32_e32 v101, v17
	s_nop 0
	v_lshlrev_b32_e32 v8, 16, v96
	v_mul_f32_e32 v17, v4, v100
	v_and_b32_e32 v9, 0xffff0000, v96
	s_nop 0
	v_lshlrev_b32_e32 v96, 16, v93
	v_and_b32_e32 v97, 0xffff0000, v93
	v_med3_f32 v130, v17, s52, v224
	v_mul_f32_e32 v17, v5, v101
	v_med3_f32 v131, v17, s52, v224
	v_pk_mul_f32 v[100:101], v[100:101], v[96:97]
	v_pk_mul_f32 v[96:97], v[130:131], v[96:97]
	v_cvt_pk_bf16_f32 v17, v100, v101
	v_rcp_f32_e32 v100, v130
	v_rcp_f32_e32 v101, v131
	ds_write_b32 v105, v17 offset:544
	v_cvt_pk_bf16_f32 v17, v96, v97
	v_add_u32_e32 v93, v2, v27
	v_pk_mul_f32 v[8:9], v[100:101], v[8:9]
	s_nop 0
	v_lshlrev_b32_e32 v96, 16, v95
	v_cvt_pk_bf16_f32 v8, v8, v9
	ds_write2st64_b32 v93, v17, v8 offset0:68 offset1:136
	v_add_f32_e32 v17, v119, v6
	v_exp_f32_e32 v100, v17
	v_add_f32_e32 v17, v106, v3
	v_exp_f32_e32 v101, v17
	v_and_b32_e32 v97, 0xffff0000, v95
	v_mul_f32_e32 v17, v4, v100
	v_med3_f32 v130, v17, s52, v224
	v_mul_f32_e32 v17, v5, v101
	v_med3_f32 v131, v17, s52, v224
	v_pk_mul_f32 v[100:101], v[100:101], v[96:97]
	v_lshlrev_b32_e32 v8, 16, v98
	v_cvt_pk_bf16_f32 v17, v100, v101
	v_rcp_f32_e32 v100, v130
	v_rcp_f32_e32 v101, v131
	v_and_b32_e32 v9, 0xffff0000, v98
	v_pk_mul_f32 v[96:97], v[130:131], v[96:97]
	ds_write_b32 v105, v17 offset:816
	v_pk_mul_f32 v[8:9], v[100:101], v[8:9]
	v_cvt_pk_bf16_f32 v17, v96, v97
	v_add_u32_e32 v93, v2, v28
	v_cvt_pk_bf16_f32 v8, v8, v9
	ds_write2st64_b32 v93, v17, v8 offset0:68 offset1:136
	v_add_f32_e32 v17, v120, v6
	v_exp_f32_e32 v96, v17
	v_add_f32_e32 v17, v108, v3
	v_exp_f32_e32 v97, v17
	s_nop 0
	v_lshlrev_b32_e32 v8, 16, v94
	v_mul_f32_e32 v17, v4, v96
	v_and_b32_e32 v9, 0xffff0000, v94
	s_nop 0
	v_lshlrev_b32_e32 v94, 16, v92
	v_and_b32_e32 v95, 0xffff0000, v92
	v_med3_f32 v92, v17, s52, v224
	v_mul_f32_e32 v17, v5, v97
	v_med3_f32 v93, v17, s52, v224
	v_pk_mul_f32 v[96:97], v[96:97], v[94:95]
	s_nop 0
	v_cvt_pk_bf16_f32 v17, v96, v97
	v_rcp_f32_e32 v96, v92
	v_rcp_f32_e32 v97, v93
	v_pk_mul_f32 v[92:93], v[92:93], v[94:95]
	ds_write_b32 v105, v17 offset:1088
	v_cvt_pk_bf16_f32 v17, v92, v93
	v_pk_mul_f32 v[8:9], v[96:97], v[8:9]
	v_add_u32_e32 v92, v2, v29
	v_cvt_pk_bf16_f32 v8, v8, v9
	ds_write2st64_b32 v92, v17, v8 offset0:68 offset1:136
	v_add_f32_e32 v17, v121, v6
	v_exp_f32_e32 v94, v17
	v_add_f32_e32 v17, v109, v3
	v_exp_f32_e32 v95, v17
	s_nop 0
	v_lshlrev_b32_e32 v92, 16, v90
	v_mul_f32_e32 v17, v4, v94
	v_and_b32_e32 v93, 0xffff0000, v90
	v_med3_f32 v90, v17, s52, v224
	v_mul_f32_e32 v17, v5, v95
	v_lshlrev_b32_e32 v8, 16, v91
	v_and_b32_e32 v9, 0xffff0000, v91
	v_med3_f32 v91, v17, s52, v224
	v_pk_mul_f32 v[94:95], v[94:95], v[92:93]
	v_add_u32_e32 v96, s16, v7
	v_cvt_pk_bf16_f32 v17, v94, v95
	v_rcp_f32_e32 v94, v90
	v_rcp_f32_e32 v95, v91
	v_pk_mul_f32 v[90:91], v[90:91], v[92:93]
	ds_write_b32 v105, v17 offset:1360
	v_cvt_pk_bf16_f32 v17, v90, v91
	v_pk_mul_f32 v[8:9], v[94:95], v[8:9]
	v_add_u32_e32 v90, v2, v30
	v_cvt_pk_bf16_f32 v8, v8, v9
	ds_write2st64_b32 v90, v17, v8 offset0:68 offset1:136
	v_add_f32_e32 v17, v122, v6
	v_exp_f32_e32 v92, v17
	v_add_f32_e32 v17, v111, v3
	v_exp_f32_e32 v93, v17
	s_nop 0
	v_lshlrev_b32_e32 v90, 16, v86
	v_mul_f32_e32 v17, v4, v92
	v_and_b32_e32 v91, 0xffff0000, v86
	v_med3_f32 v94, v17, s52, v224
	v_mul_f32_e32 v17, v5, v93
	v_med3_f32 v95, v17, s52, v224
	v_pk_mul_f32 v[92:93], v[92:93], v[90:91]
	v_lshlrev_b32_e32 v8, 16, v89
	v_cvt_pk_bf16_f32 v17, v92, v93
	v_rcp_f32_e32 v92, v94
	v_rcp_f32_e32 v93, v95
	v_and_b32_e32 v9, 0xffff0000, v89
	v_pk_mul_f32 v[90:91], v[94:95], v[90:91]
	ds_write_b32 v96, v17
	v_pk_mul_f32 v[8:9], v[92:93], v[8:9]
	v_cvt_pk_bf16_f32 v17, v90, v91
	v_add_u32_e32 v86, v2, v31
	v_cvt_pk_bf16_f32 v8, v8, v9
	ds_write2st64_b32 v86, v17, v8 offset0:68 offset1:136
	v_add_f32_e32 v17, v123, v6
	s_nop 0
	v_lshlrev_b32_e32 v8, 16, v88
	v_and_b32_e32 v9, 0xffff0000, v88
	v_exp_f32_e32 v88, v17
	v_add_f32_e32 v17, v112, v3
	v_exp_f32_e32 v89, v17
	s_nop 0
	v_lshlrev_b32_e32 v86, 16, v87
	v_mul_f32_e32 v17, v4, v88
	v_and_b32_e32 v87, 0xffff0000, v87
	v_med3_f32 v90, v17, s52, v224
	v_mul_f32_e32 v17, v5, v89
	v_med3_f32 v91, v17, s52, v224
	v_pk_mul_f32 v[88:89], v[88:89], v[86:87]
	v_pk_mul_f32 v[86:87], v[90:91], v[86:87]
	v_cvt_pk_bf16_f32 v17, v88, v89
	v_rcp_f32_e32 v88, v90
	v_rcp_f32_e32 v89, v91
	ds_write_b32 v96, v17 offset:272
	v_cvt_pk_bf16_f32 v17, v86, v87
	v_add_u32_e32 v86, v2, v33
	v_pk_mul_f32 v[8:9], v[88:89], v[8:9]
	s_nop 0
	v_cvt_pk_bf16_f32 v8, v8, v9
	ds_write2st64_b32 v86, v17, v8 offset0:68 offset1:136
	v_add_f32_e32 v17, v124, v6
	v_exp_f32_e32 v86, v17
	v_add_f32_e32 v17, v113, v3
	v_exp_f32_e32 v87, v17
	s_nop 0
	v_lshlrev_b32_e32 v8, 16, v84
	v_mul_f32_e32 v17, v4, v86
	v_and_b32_e32 v9, 0xffff0000, v84
	s_nop 0
	v_lshlrev_b32_e32 v84, 16, v85
	v_and_b32_e32 v85, 0xffff0000, v85
	v_med3_f32 v88, v17, s52, v224
	v_mul_f32_e32 v17, v5, v87
	v_med3_f32 v89, v17, s52, v224
	v_pk_mul_f32 v[86:87], v[86:87], v[84:85]
	v_pk_mul_f32 v[84:85], v[88:89], v[84:85]
	v_cvt_pk_bf16_f32 v17, v86, v87
	v_rcp_f32_e32 v86, v88
	v_rcp_f32_e32 v87, v89
	ds_write_b32 v96, v17 offset:544
	v_cvt_pk_bf16_f32 v17, v84, v85
	v_add_u32_e32 v84, v2, v34
	v_pk_mul_f32 v[8:9], v[86:87], v[8:9]
	s_nop 0
	v_and_b32_e32 v85, 0xffff0000, v72
	v_cvt_pk_bf16_f32 v8, v8, v9
	ds_write2st64_b32 v84, v17, v8 offset0:68 offset1:136
	v_add_f32_e32 v17, v125, v6
	v_exp_f32_e32 v86, v17
	v_add_f32_e32 v17, v114, v3
	v_exp_f32_e32 v87, v17
	v_lshlrev_b32_e32 v84, 16, v72
	v_mul_f32_e32 v17, v4, v86
	v_med3_f32 v88, v17, s52, v224
	v_mul_f32_e32 v17, v5, v87
	v_med3_f32 v89, v17, s52, v224
	v_pk_mul_f32 v[86:87], v[86:87], v[84:85]
	v_lshlrev_b32_e32 v8, 16, v71
	v_cvt_pk_bf16_f32 v17, v86, v87
	v_rcp_f32_e32 v86, v88
	v_rcp_f32_e32 v87, v89
	v_and_b32_e32 v9, 0xffff0000, v71
	v_pk_mul_f32 v[84:85], v[88:89], v[84:85]
	ds_write_b32 v96, v17 offset:816
	v_pk_mul_f32 v[8:9], v[86:87], v[8:9]
	v_cvt_pk_bf16_f32 v17, v84, v85
	v_add_u32_e32 v71, v2, v35
	v_cvt_pk_bf16_f32 v8, v8, v9
	ds_write2st64_b32 v71, v17, v8 offset0:68 offset1:136
	v_add_f32_e32 v17, v126, v6
	v_exp_f32_e32 v86, v17
	v_add_f32_e32 v17, v115, v3
	v_exp_f32_e32 v87, v17
	s_nop 0
	v_lshlrev_b32_e32 v84, 16, v51
	v_mul_f32_e32 v17, v4, v86
	v_and_b32_e32 v85, 0xffff0000, v51
	v_med3_f32 v88, v17, s52, v224
	v_mul_f32_e32 v17, v5, v87
	v_med3_f32 v89, v17, s52, v224
	v_pk_mul_f32 v[86:87], v[86:87], v[84:85]
	v_lshlrev_b32_e32 v8, 16, v48
	v_cvt_pk_bf16_f32 v17, v86, v87
	v_rcp_f32_e32 v86, v88
	v_rcp_f32_e32 v87, v89
	v_and_b32_e32 v9, 0xffff0000, v48
	v_pk_mul_f32 v[84:85], v[88:89], v[84:85]
	ds_write_b32 v96, v17 offset:1088
	v_pk_mul_f32 v[8:9], v[86:87], v[8:9]
	v_cvt_pk_bf16_f32 v17, v84, v85
	v_add_u32_e32 v48, v2, v36
	v_cvt_pk_bf16_f32 v8, v8, v9
	ds_write2st64_b32 v48, v17, v8 offset0:68 offset1:136
	v_add_f32_e32 v17, v127, v6
	v_exp_f32_e32 v86, v17
	v_add_f32_e32 v17, v116, v3
	v_exp_f32_e32 v87, v17
	s_nop 0
	v_lshlrev_b32_e32 v84, 16, v59
	v_mul_f32_e32 v17, v4, v86
	v_and_b32_e32 v85, 0xffff0000, v59
	v_med3_f32 v88, v17, s52, v224
	v_mul_f32_e32 v17, v5, v87
	v_med3_f32 v89, v17, s52, v224
	v_pk_mul_f32 v[86:87], v[86:87], v[84:85]
	v_lshlrev_b32_e32 v8, 16, v52
	v_cvt_pk_bf16_f32 v17, v86, v87
	v_rcp_f32_e32 v86, v88
	v_rcp_f32_e32 v87, v89
	v_and_b32_e32 v9, 0xffff0000, v52
	v_pk_mul_f32 v[84:85], v[88:89], v[84:85]
	ds_write_b32 v96, v17 offset:1360
	v_pk_mul_f32 v[8:9], v[86:87], v[8:9]
	v_cvt_pk_bf16_f32 v17, v84, v85
	v_add_u32_e32 v48, v2, v37
	v_cvt_pk_bf16_f32 v8, v8, v9
	ds_write2st64_b32 v48, v17, v8 offset0:68 offset1:136
	v_add_f32_e32 v17, v128, v6
	v_exp_f32_e32 v84, v17
	v_add_f32_e32 v17, v117, v3
	v_exp_f32_e32 v85, v17
	s_nop 0
	v_lshlrev_b32_e32 v8, 16, v44
	v_mul_f32_e32 v17, v4, v84
	v_and_b32_e32 v9, 0xffff0000, v44
	s_nop 0
	v_lshlrev_b32_e32 v44, 16, v45
	v_and_b32_e32 v45, 0xffff0000, v45
	v_med3_f32 v86, v17, s52, v224
	v_mul_f32_e32 v17, v5, v85
	v_med3_f32 v87, v17, s52, v224
	v_pk_mul_f32 v[84:85], v[84:85], v[44:45]
	v_add_u32_e32 v48, s17, v7
	v_cvt_pk_bf16_f32 v17, v84, v85
	v_rcp_f32_e32 v84, v86
	v_rcp_f32_e32 v85, v87
	v_pk_mul_f32 v[44:45], v[86:87], v[44:45]
	ds_write_b32 v48, v17
	v_cvt_pk_bf16_f32 v7, v44, v45
	v_pk_mul_f32 v[8:9], v[84:85], v[8:9]
	v_add_u32_e32 v17, v2, v38
	v_cvt_pk_bf16_f32 v8, v8, v9
	ds_write2st64_b32 v17, v7, v8 offset0:68 offset1:136
	v_add_f32_e32 v7, v129, v6
	v_exp_f32_e32 v44, v7
	v_add_f32_e32 v7, v15, v3
	v_exp_f32_e32 v45, v7
	s_nop 0
	v_lshlrev_b32_e32 v8, 16, v42
	v_mul_f32_e32 v7, v4, v44
	v_and_b32_e32 v9, 0xffff0000, v42
	s_nop 0
	v_lshlrev_b32_e32 v42, 16, v43
	v_and_b32_e32 v43, 0xffff0000, v43
	v_med3_f32 v84, v7, s52, v224
	v_mul_f32_e32 v7, v5, v45
	v_med3_f32 v85, v7, s52, v224
	v_pk_mul_f32 v[44:45], v[44:45], v[42:43]
	v_pk_mul_f32 v[42:43], v[84:85], v[42:43]
	v_cvt_pk_bf16_f32 v7, v44, v45
	v_rcp_f32_e32 v44, v84
	v_rcp_f32_e32 v45, v85
	v_add_f32_e32 v6, v16, v6
	ds_write_b32 v48, v7 offset:272
	v_cvt_pk_bf16_f32 v7, v42, v43
	v_pk_mul_f32 v[8:9], v[44:45], v[8:9]
	v_add_u32_e32 v17, v2, v40
	v_cvt_pk_bf16_f32 v8, v8, v9
	v_exp_f32_e32 v6, v6
	v_add_f32_e32 v3, v19, v3
	ds_write2st64_b32 v17, v7, v8 offset0:68 offset1:136
	v_exp_f32_e32 v7, v3
	v_mul_f32_e32 v3, v4, v6
	s_waitcnt vmcnt(0)
	v_lshlrev_b32_e32 v42, 16, v39
	v_and_b32_e32 v43, 0xffff0000, v39
	v_med3_f32 v4, v3, s52, v224
	v_mul_f32_e32 v3, v5, v7
	v_med3_f32 v5, v3, s52, v224
	v_pk_mul_f32 v[6:7], v[6:7], v[42:43]
	v_lshlrev_b32_e32 v8, 16, v32
	v_cvt_pk_bf16_f32 v3, v6, v7
	v_rcp_f32_e32 v6, v4
	v_rcp_f32_e32 v7, v5
	v_and_b32_e32 v9, 0xffff0000, v32
	v_pk_mul_f32 v[4:5], v[4:5], v[42:43]
	ds_write_b32 v48, v3 offset:544
	v_cvt_pk_bf16_f32 v4, v4, v5
	v_add_u32_e32 v5, v2, v41
	v_pk_mul_f32 v[2:3], v[6:7], v[8:9]
	v_mov_b32_e32 v32, v62
	v_cvt_pk_bf16_f32 v2, v2, v3
	ds_write2st64_b32 v5, v4, v2 offset0:68 offset1:136
	s_waitcnt vmcnt(0)
	v_mov_b32_e32 v42, v76
	v_mov_b32_e32 v44, v74
	v_mov_b32_e32 v52, v73
	v_mov_b32_e32 v48, v70
	v_mov_b32_e32 v71, v66
	v_mov_b32_e32 v84, v64
	v_mov_b32_e32 v88, v63
	v_mov_b32_e32 v93, v60
	v_mov_b32_e32 v95, v65
	v_mov_b32_e32 v92, v67
	v_mov_b32_e32 v90, v68
	v_mov_b32_e32 v86, v69
	v_mov_b32_e32 v87, v75
	v_mov_b32_e32 v85, v77
	v_mov_b32_e32 v72, v78
	v_mov_b32_e32 v51, v79
	v_mov_b32_e32 v59, v80
	v_mov_b32_e32 v45, v81
	v_mov_b32_e32 v43, v82
	v_mov_b32_e32 v39, v83
	v_mov_b32_e32 v110, v46
	v_mov_b32_e32 v105, v47
	v_mov_b32_e32 v100, v49
	v_mov_b32_e32 v96, v50
	v_mov_b32_e32 v98, v53
	v_mov_b32_e32 v94, v54
	v_mov_b32_e32 v91, v56
	v_mov_b32_e32 v89, v61
	v_mov_b32_e32 v107, v55
	v_mov_b32_e32 v101, v57
	v_mov_b32_e32 v97, v58
.LBB0_869:
	s_add_i32 s18, s18, 1
	s_waitcnt lgkmcnt(0)
	s_barrier
	s_barrier
	s_add_u32 s8, s8, 0x10000
	s_addc_u32 s9, s9, 0
	s_cmp_eq_u32 s8, 0x210000
	s_cbranch_scc1 .LBB0_756

.LBB0_873:
	s_nop 0
	v_and_b32_e32 v2, 0xffff0000, v110
	v_sub_f32_e32 v2, 1.0, v2
	v_max_f32_e32 v2, 0xda24260, v2
	v_log_f32_e32 v2, v2
	v_lshlrev_b32_e32 v1, 16, v110
	v_sub_f32_e32 v1, 1.0, v1
	v_max_f32_e32 v1, 0xda24260, v1
	v_add_f32_e32 v99, 0, v2
	s_nop 0
	v_and_b32_e32 v2, 0xffff0000, v105
	v_sub_f32_e32 v2, 1.0, v2
	v_max_f32_e32 v2, 0xda24260, v2
	v_log_f32_e32 v2, v2
	v_log_f32_e32 v14, v1
	v_lshlrev_b32_e32 v1, 16, v105
	v_sub_f32_e32 v1, 1.0, v1
	v_add_f32_e32 v102, v2, v99
	s_nop 0
	v_and_b32_e32 v2, 0xffff0000, v100
	v_sub_f32_e32 v2, 1.0, v2
	v_max_f32_e32 v2, 0xda24260, v2
	v_log_f32_e32 v2, v2
	v_max_f32_e32 v1, 0xda24260, v1
	v_log_f32_e32 v3, v1
	v_lshlrev_b32_e32 v1, 16, v100
	v_add_f32_e32 v103, v2, v102
	s_nop 0
	v_and_b32_e32 v2, 0xffff0000, v96
	v_sub_f32_e32 v2, 1.0, v2
	v_max_f32_e32 v2, 0xda24260, v2
	v_log_f32_e32 v2, v2
	v_sub_f32_e32 v1, 1.0, v1
	v_max_f32_e32 v1, 0xda24260, v1
	v_log_f32_e32 v4, v1
	v_add_f32_e32 v104, v2, v103
	s_nop 0
	v_and_b32_e32 v2, 0xffff0000, v98
	v_sub_f32_e32 v2, 1.0, v2
	v_max_f32_e32 v2, 0xda24260, v2
	v_log_f32_e32 v2, v2
	v_lshlrev_b32_e32 v1, 16, v96
	v_sub_f32_e32 v1, 1.0, v1
	v_max_f32_e32 v1, 0xda24260, v1
	v_add_f32_e32 v106, v2, v104
	s_nop 0
	v_and_b32_e32 v2, 0xffff0000, v94
	v_sub_f32_e32 v2, 1.0, v2
	v_max_f32_e32 v2, 0xda24260, v2
	v_log_f32_e32 v2, v2
	v_log_f32_e32 v5, v1
	v_lshlrev_b32_e32 v1, 16, v98
	v_sub_f32_e32 v1, 1.0, v1
	v_add_f32_e32 v108, v2, v106
	s_nop 0
	v_and_b32_e32 v2, 0xffff0000, v91
	v_sub_f32_e32 v2, 1.0, v2
	v_max_f32_e32 v2, 0xda24260, v2
	v_log_f32_e32 v2, v2
	v_max_f32_e32 v1, 0xda24260, v1
	v_log_f32_e32 v6, v1
	v_lshlrev_b32_e32 v1, 16, v94
	v_add_f32_e32 v109, v2, v108
	s_nop 0
	v_and_b32_e32 v2, 0xffff0000, v89
	v_sub_f32_e32 v2, 1.0, v2
	v_max_f32_e32 v2, 0xda24260, v2
	v_log_f32_e32 v2, v2
	v_sub_f32_e32 v1, 1.0, v1
	v_max_f32_e32 v1, 0xda24260, v1
	v_log_f32_e32 v7, v1
	v_add_f32_e32 v111, v2, v109
	s_nop 0
	v_and_b32_e32 v2, 0xffff0000, v88
	v_sub_f32_e32 v2, 1.0, v2
	v_max_f32_e32 v2, 0xda24260, v2
	v_log_f32_e32 v2, v2
	v_lshlrev_b32_e32 v1, 16, v91
	v_sub_f32_e32 v1, 1.0, v1
	v_max_f32_e32 v1, 0xda24260, v1
	v_add_f32_e32 v112, v111, v2
	s_nop 0
	v_and_b32_e32 v2, 0xffff0000, v84
	v_sub_f32_e32 v2, 1.0, v2
	v_max_f32_e32 v2, 0xda24260, v2
	v_log_f32_e32 v2, v2
	v_log_f32_e32 v8, v1
	v_lshlrev_b32_e32 v1, 16, v89
	v_sub_f32_e32 v1, 1.0, v1
	v_add_f32_e32 v113, v112, v2
	s_nop 0
	v_and_b32_e32 v2, 0xffff0000, v71
	v_sub_f32_e32 v2, 1.0, v2
	v_max_f32_e32 v2, 0xda24260, v2
	v_log_f32_e32 v2, v2
	v_max_f32_e32 v1, 0xda24260, v1
	v_log_f32_e32 v9, v1
	v_lshlrev_b32_e32 v1, 16, v88
	v_add_f32_e32 v114, v113, v2
	s_nop 0
	v_and_b32_e32 v2, 0xffff0000, v48
	v_sub_f32_e32 v2, 1.0, v2
	v_sub_f32_e32 v1, 1.0, v1
	v_max_f32_e32 v2, 0xda24260, v2
	v_max_f32_e32 v1, 0xda24260, v1
	v_log_f32_e32 v2, v2
	v_log_f32_e32 v16, v1
	v_lshlrev_b32_e32 v1, 16, v84
	v_sub_f32_e32 v1, 1.0, v1
	v_max_f32_e32 v1, 0xda24260, v1
	v_log_f32_e32 v17, v1
	v_lshlrev_b32_e32 v1, 16, v71
	v_add_f32_e32 v115, v114, v2
	s_nop 0
	v_and_b32_e32 v2, 0xffff0000, v52
	v_sub_f32_e32 v1, 1.0, v1
	v_sub_f32_e32 v2, 1.0, v2
	v_max_f32_e32 v1, 0xda24260, v1
	v_max_f32_e32 v2, 0xda24260, v2
	v_log_f32_e32 v125, v1
	v_lshlrev_b32_e32 v1, 16, v48
	v_log_f32_e32 v2, v2
	v_sub_f32_e32 v1, 1.0, v1
	v_max_f32_e32 v1, 0xda24260, v1
	v_log_f32_e32 v126, v1
	v_lshlrev_b32_e32 v1, 16, v52
	v_sub_f32_e32 v1, 1.0, v1
	v_add_f32_e32 v116, v115, v2
	s_nop 0
	v_and_b32_e32 v2, 0xffff0000, v44
	v_max_f32_e32 v1, 0xda24260, v1
	v_sub_f32_e32 v2, 1.0, v2
	v_log_f32_e32 v127, v1
	v_lshlrev_b32_e32 v1, 16, v44
	v_max_f32_e32 v2, 0xda24260, v2
	v_log_f32_e32 v2, v2
	v_sub_f32_e32 v1, 1.0, v1
	v_max_f32_e32 v1, 0xda24260, v1
	v_log_f32_e32 v128, v1
	s_nop 0
	v_lshlrev_b32_e32 v1, 16, v42
	v_sub_f32_e32 v1, 1.0, v1
	v_add_f32_e32 v117, v116, v2
	v_and_b32_e32 v2, 0xffff0000, v42
	v_max_f32_e32 v1, 0xda24260, v1
	v_sub_f32_e32 v2, 1.0, v2
	v_log_f32_e32 v129, v1
	s_nop 0
	v_and_b32_e32 v1, 0xffff0000, v32
	v_max_f32_e32 v2, 0xda24260, v2
	v_sub_f32_e32 v1, 1.0, v1
	v_log_f32_e32 v2, v2
	v_max_f32_e32 v1, 0xda24260, v1
	v_log_f32_e32 v1, v1
	s_add_i32 s21, s20, s13
	v_add_f32_e32 v15, v117, v2
	v_lshlrev_b32_e32 v2, 16, v32
	v_pk_add_f32 v[18:19], v[14:15], v[0:1]
	v_sub_f32_e32 v2, 1.0, v2
	v_add_f32_e32 v1, v3, v18
	v_add_f32_e32 v14, v4, v1
	v_add_f32_e32 v118, v5, v14
	v_add_f32_e32 v119, v6, v118
	v_add_f32_e32 v120, v7, v119
	v_add_f32_e32 v121, v8, v120
	v_add_f32_e32 v122, v9, v121
	v_add_f32_e32 v123, v122, v16
	v_add_f32_e32 v124, v123, v17
	v_max_f32_e32 v2, 0xda24260, v2
	v_add_f32_e32 v125, v124, v125
	v_log_f32_e32 v2, v2
	v_add_f32_e32 v126, v125, v126
	v_add_f32_e32 v127, v126, v127
	v_add_f32_e32 v128, v127, v128
	v_add_f32_e32 v129, v128, v129
	v_add_f32_e32 v16, v129, v2
	v_mov_b32_e32 v17, v19
	v_add_u32_e32 v2, s21, v20
	ds_write_b64 v2, v[16:17]
.LBB0_874:
	s_waitcnt lgkmcnt(0)
	s_barrier
	s_andn2_b64 vcc, exec, s[10:11]
	s_cbranch_vccnz .LBB0_869
	v_add_u32_e32 v17, s20, v20
	ds_read2st64_b64 v[2:5], v17 offset1:1
	ds_read2st64_b64 v[6:9], v17 offset0:2 offset1:3
	s_andn2_b64 vcc, exec, s[0:1]
	s_waitcnt lgkmcnt(1)
	v_add_f32_e32 v130, 0, v2
	v_add_f32_e32 v3, 0, v3
	v_add_f32_e32 v2, v130, v4
	v_add_f32_e32 v131, v3, v5
	s_waitcnt lgkmcnt(0)
	v_add_f32_e32 v2, v2, v6
	v_add_f32_e32 v131, v131, v7
	v_add_f32_e32 v2, v2, v8
	v_add_f32_e32 v8, v131, v9
	s_cbranch_vccnz .LBB0_868
	v_exp_f32_e32 v132, v2
	v_exp_f32_e32 v133, v8
	ds_write_b64 v17, v[132:133] offset:2048
	s_branch .LBB0_868
